# GEMM tile start: de-phase sleep of the odd co-resident workgroup 10 -> 4
# speedup vs baseline: 1.0047x; 1.0009x over previous
.LBB0_242:
	s_andn2_b64 vcc, exec, s[48:49]
	s_cbranch_vccnz .LBB0_236
	s_lshl_b32 s48, s6, 8
	s_lshl_b32 s46, s80, 7
	s_ashr_i32 s49, s48, 31
	s_ashr_i32 s47, s46, 31
	s_lshl_b64 s[10:11], s[48:49], 11
	s_lshl_b64 s[50:51], s[46:47], 11
	s_add_u32 s10, s94, s10
	v_readfirstlane_b32 s5, v147
	v_add_u32_e32 v2, 0x400, v147
	s_addc_u32 s11, s95, s11
	v_mov_b32_e32 v0, v135
	s_mov_b32 m0, s5
	v_readfirstlane_b32 s5, v2
	v_add_u32_e32 v2, 0x800, v147
	v_mov_b32_e32 v130, v142
	global_load_lds_dwordx4 v0, s[10:11]
	s_mov_b32 m0, s5
	v_readfirstlane_b32 s5, v2
	v_add_u32_e32 v2, 0xc00, v147
	v_mov_b32_e32 v132, v143
	global_load_lds_dwordx4 v130, s[10:11]
	s_mov_b32 m0, s5
	v_readfirstlane_b32 s5, v2
	v_add_u32_e32 v2, 0x4000, v148
	s_add_u32 s52, s54, s50
	v_mov_b32_e32 v136, v144
	global_load_lds_dwordx4 v132, s[10:11]
	s_mov_b32 m0, s5
	v_readfirstlane_b32 s5, v2
	v_add_u32_e32 v2, 0x4400, v148
	s_addc_u32 s53, s55, s51
	v_mov_b32_e32 v138, v145
	global_load_lds_dwordx4 v136, s[10:11]
	s_mov_b32 m0, s5
	v_readfirstlane_b32 s5, v2
	v_mov_b32_e32 v140, v146
	global_load_lds_dwordx4 v138, s[52:53]
	s_mov_b32 m0, s5
	v_add_u32_e32 v4, 0x6000, v147
	v_mov_b32_e32 v131, v1
	global_load_lds_dwordx4 v140, s[52:53]
	v_readfirstlane_b32 s5, v4
	v_lshl_add_u64 v[2:3], s[10:11], 0, v[0:1]
	v_lshl_add_u64 v[2:3], v[2:3], 0, s[60:61]
	s_mov_b32 m0, s5
	v_add_u32_e32 v4, 0x6400, v147
	global_load_lds_dwordx4 v[2:3], off
	v_readfirstlane_b32 s5, v4
	v_lshl_add_u64 v[2:3], s[10:11], 0, v[130:131]
	v_lshl_add_u64 v[2:3], v[2:3], 0, s[60:61]
	s_mov_b32 m0, s5
	v_mov_b32_e32 v133, v1
	v_add_u32_e32 v4, 0x6800, v147
	global_load_lds_dwordx4 v[2:3], off
	v_readfirstlane_b32 s5, v4
	v_lshl_add_u64 v[2:3], s[10:11], 0, v[132:133]
	v_lshl_add_u64 v[2:3], v[2:3], 0, s[60:61]
	s_mov_b32 m0, s5
	v_mov_b32_e32 v137, v1
	v_add_u32_e32 v4, 0x6c00, v147
	global_load_lds_dwordx4 v[2:3], off
	v_readfirstlane_b32 s5, v4
	v_lshl_add_u64 v[2:3], s[10:11], 0, v[136:137]
	v_lshl_add_u64 v[2:3], v[2:3], 0, s[60:61]
	s_mov_b32 m0, s5
	v_mov_b32_e32 v139, v1
	v_add_u32_e32 v4, 0xa000, v148
	global_load_lds_dwordx4 v[2:3], off
	v_readfirstlane_b32 s5, v4
	v_lshl_add_u64 v[2:3], s[52:53], 0, v[138:139]
	v_lshl_add_u64 v[2:3], v[2:3], 0, s[86:87]
	s_mov_b32 m0, s5
	v_mov_b32_e32 v141, v1
	v_add_u32_e32 v4, 0xa400, v148
	global_load_lds_dwordx4 v[2:3], off
	v_readfirstlane_b32 s5, v4
	v_lshl_add_u64 v[2:3], s[52:53], 0, v[140:141]
	v_lshl_add_u64 v[2:3], v[2:3], 0, s[86:87]
	s_mov_b32 m0, s5
	s_andn2_b64 vcc, exec, s[28:29]
	global_load_lds_dwordx4 v[2:3], off
	s_cbranch_vccnz .LBB0_245
	s_sleep 4
